# v6 + GEMM wave halves no longer re-synchronise around the epilogue (per-tile barrier pair removed, balancing barrier once at phase exit)
# speedup vs baseline: 1.0033x; 1.0033x over previous
; #define PG8_BAR __builtin_amdgcn_s_barrier()
; __device__ __forceinline__ void epi_store(const f32x4 (&acc)[2][2][4][2], const Unit& u, int wr, int wc, int fr, int fq, const EpiP& e) {
;     ...
;     const int col0 = u.pn * BM + wc * 32 + 4 * fq;
; #pragma unroll
;     for (int bj = 0; bj < 2; ++bj) {
;         const int c = col0 + bj * HALF;
;         int kind = 0;
;         if (e.mode == 2) { if (c < 2048) kind = ((c >> 5) & 1) ? 2 : 1; }
;         else { const int d = c % 192; if (d >= 128) kind = (d >= 160) ? 2 : 1; }
; __device__ __forceinline__ void gemm_phase(LAS unsigned char* lds, const GemmP g, const EpiP e) {
;     ...
;         if (wr == 0) PG8_BAR;
;         epi_store(acc, cur, wr, wc, fr, fq, e);
.LBB0_395:
.LBB0_397:
	s_lshl_b32 s18, s87, 8
	v_readlane_b32 s3, v254, 56
	v_readlane_b32 s20, v255, 11
	s_add_i32 s18, s18, s3
	v_readlane_b32 s21, v255, 12
	v_or_b32_e32 v98, s18, v151
	s_lshl_b32 s43, s85, 8
	s_mov_b64 s[16:17], -1
	s_and_b64 vcc, exec, s[20:21]
	s_cbranch_vccz .LBB0_440
	v_readfirstlane_b32 s16, v159
	v_and_b32_e32 v217, 15, v159
	v_bfe_u32 v219, v159, 4, 2
	s_lshr_b32 s16, s16, 6
	s_and_b32 s17, s16, 3
	s_lshr_b32 s16, s16, 2
	s_mul_i32 s18, s87, s70
	s_lshl_b32 s18, s18, 9
	s_lshl_b32 s19, s85, 9
	s_add_u32 s18, s18, s19
	s_add_u32 s100, s74, s18
	s_addc_u32 s101, s75, 0
	s_lshl_b32 s18, s16, 6
	v_or_b32_e32 v218, s18, v217
	v_mul_lo_u32 v218, v218, s70
	v_and_b32_e32 v220, 1, v219
	v_mul_u32_u24_e32 v220, 12, v220
	v_lshl_add_u32 v220, v219, 2, v220
	s_lshl_b32 s18, s17, 5
	v_add_u32_e32 v220, s18, v220
	v_add_lshl_u32 v216, v218, v220, 1
	s_lshl_b32 s19, s70, 5
	v_lshlrev_b32_e32 v221, 5, v219
	v_lshl_or_b32 v222, v217, 7, v221
	v_readlane_b32 s22, v255, 15
	v_readlane_b32 s23, v255, 16
	s_and_b64 vcc, exec, s[22:23]
	s_cbranch_vccnz .Lrp_m3
	s_and_b32 s20, s17, 1
	s_add_i32 s20, s20, 1
	s_cmp_lt_u32 s85, 8
	s_cselect_b32 s20, s20, 0
	s_mov_b32 s21, s20
	s_branch .Lrp_kdone

; #define PG8_WAIT_V(n) asm volatile("s_waitcnt vmcnt(" #n ")" ::: "memory")
; #define PG8_BAR __builtin_amdgcn_s_barrier()
; __device__ __forceinline__ void gemm_phase(LAS unsigned char* lds, const GemmP g, const EpiP e) {
;     ...
;         if (wr == 1) PG8_BAR;
;     }
;     PG8_WAIT_V(0);
;     PG8_BAR;
.LBB0_574:
	s_branch .LBB0_370
.LBB0_576:
	v_readlane_b32 s16, v254, 63
	v_readlane_b32 s17, v255, 0
	s_and_b64 vcc, exec, s[16:17]
	s_cbranch_vccz .Lnb_exit
	s_barrier
.Lnb_exit:
	s_waitcnt vmcnt(0)
	v_readlane_b32 s88, v253, 60
	s_mov_b32 s94, 0x3b800000
	v_readlane_b32 s78, v254, 0
	v_readlane_b32 s90, v253, 58
	v_readlane_b32 s4, v253, 0
	v_readlane_b32 s89, v253, 61
	s_mov_b32 s95, 0x3b2aaaab
	s_movk_i32 s77, 0xc00
	s_movk_i32 s84, 0x180
	s_mov_b32 s86, 0x2aaaaaab
	v_readlane_b32 s79, v254, 1
	s_movk_i32 s37, 0x7fff
	s_movk_i32 s73, 0x47ff
	v_readlane_b32 s68, v255, 18
	s_barrier
	v_readlane_b32 s91, v253, 59
	v_readlane_b32 s5, v253, 1
